# FoX hot loop instruction removals: m0 write ahead of the slot's two LDS reads (no s_nop 0 before the LDS-DMA), one lgkmcnt wait per QK MFMA pair, no NaN-quieting self-max in the row max
# baseline (speedup 1.0000x reference)
.Lfx_body:
	s_cmp_lt_u32 s62, 0x4000005e
	s_cselect_b64 s[78:79], -1, 0
	s_andn2_b64 vcc, exec, s[78:79]
	s_cbranch_vccnz .Lfx_h1_done
	s_andn2_b64 vcc, exec, s[80:81]
	s_cbranch_vccnz .Lfx_h1_qonly
	s_add_i32 s64, s77, s51
	v_add_u32_e32 v10, s64, v183
	v_add_u32_e32 v11, s64, v184
	v_add_u32_e32 v12, s64, v185
	v_add_u32_e32 v13, s64, v186
	s_add_i32 s65, s76, s51
	v_add_u32_e32 v14, s65, v174
	s_lshl_b32 s66, s50, 2
	s_add_i32 s66, s66, s76
	v_lshl_add_u32 v0, v144, 2, s66
	v_add_u32_e32 v0, 0x10000, v0
	s_waitcnt lgkmcnt(6)
	v_mfma_f32_32x32x16_bf16 v[64:79], v[2:5], v[196:199], v[64:79]
	ds_read_b64_tr_b16 v[220:221], v11 offset:32768
	ds_read_b64_tr_b16 v[222:223], v11 offset:34816
	s_lshl_b32 s64, s41, 7
	s_add_i32 s66, s64, 0xffffff80
	s_max_i32 s66, s66, 0
	s_mov_b32 s67, 0
	s_lshl_b64 s[28:29], s[66:67], 8
	s_add_u32 s28, s27, s28
	s_addc_u32 s29, s38, s29
	s_lshl_b64 s[68:69], s[66:67], 2
	s_add_u32 s68, s70, s68
	s_addc_u32 s69, s71, s69
	s_lshl_b64 s[30:31], s[66:67], 8
	s_add_u32 s30, s23, s30
	s_addc_u32 s31, s24, s31
	ds_read_b128 v[96:99], v0
	s_waitcnt lgkmcnt(7)
	v_mfma_f32_32x32x16_bf16 v[64:79], v[6:9], v[204:207], v[64:79]
	s_add_i32 s33, s73, s77
	s_mov_b32 m0, s33
	ds_read_b64_tr_b16 v[224:225], v11 offset:36864
	ds_read_b64_tr_b16 v[226:227], v11 offset:38912
	global_load_lds_dwordx4 v163, s[28:29]
	ds_read_b128 v[100:103], v0 offset:32
	s_waitcnt lgkmcnt(8)
	v_mfma_f32_32x32x16_bf16 v[64:79], v[212:215], v[200:203], v[64:79]
	ds_read_b64_tr_b16 v[228:229], v11 offset:40960
	ds_read_b64_tr_b16 v[230:231], v11 offset:43008
	ds_read_b128 v[80:83], v0 offset:128
	s_waitcnt lgkmcnt(9)
	v_mfma_f32_32x32x16_bf16 v[64:79], v[216:219], v[208:211], v[64:79]
	ds_read_b64_tr_b16 v[232:233], v11 offset:45056
	ds_read_b64_tr_b16 v[234:235], v11 offset:47104
	ds_read_b128 v[84:87], v0 offset:160
	s_waitcnt lgkmcnt(10)
	v_mfma_f32_32x32x16_bf16 v[48:63], v[220:223], v[196:199], v[48:63]
	s_add_i32 m0, s33, 0x400
	ds_read_b64_tr_b16 v[2:3], v12 offset:32768
	ds_read_b64_tr_b16 v[4:5], v12 offset:34816
	global_load_lds_dwordx4 v189, s[28:29]
	ds_read_b128 v[104:107], v0 offset:64
	s_waitcnt lgkmcnt(10)
	v_mfma_f32_32x32x16_bf16 v[48:63], v[224:227], v[204:207], v[48:63]
	ds_read_b64_tr_b16 v[6:7], v12 offset:36864
	ds_read_b64_tr_b16 v[8:9], v12 offset:38912
	ds_read_b128 v[108:111], v0 offset:96
	s_waitcnt lgkmcnt(10)
	v_mfma_f32_32x32x16_bf16 v[48:63], v[228:231], v[200:203], v[48:63]
	ds_read_b64_tr_b16 v[212:213], v12 offset:40960
	ds_read_b64_tr_b16 v[214:215], v12 offset:43008
	ds_read_b128 v[88:91], v0 offset:192
	s_waitcnt lgkmcnt(10)
	v_mfma_f32_32x32x16_bf16 v[48:63], v[232:235], v[208:211], v[48:63]
	s_add_i32 m0, s33, 0x800
	ds_read_b64_tr_b16 v[216:217], v12 offset:45056
	ds_read_b64_tr_b16 v[218:219], v12 offset:47104
	global_load_lds_dwordx4 v190, s[28:29]
	ds_read_b128 v[92:95], v0 offset:224
	s_waitcnt lgkmcnt(10)
	v_mfma_f32_32x32x16_bf16 v[32:47], v[2:5], v[196:199], v[32:47]
	ds_read_b64_tr_b16 v[220:221], v13 offset:32768
	ds_read_b64_tr_b16 v[222:223], v13 offset:34816
	s_waitcnt lgkmcnt(9)
	v_mfma_f32_32x32x16_bf16 v[32:47], v[6:9], v[204:207], v[32:47]
	ds_read_b64_tr_b16 v[224:225], v13 offset:36864
	ds_read_b64_tr_b16 v[226:227], v13 offset:38912
	s_waitcnt lgkmcnt(8)
	v_mfma_f32_32x32x16_bf16 v[32:47], v[212:215], v[200:203], v[32:47]
	s_add_i32 m0, s33, 0xc00
	ds_read_b64_tr_b16 v[228:229], v13 offset:40960
	ds_read_b64_tr_b16 v[230:231], v13 offset:43008
	global_load_lds_dwordx4 v191, s[28:29]
	s_waitcnt lgkmcnt(7)
	v_mfma_f32_32x32x16_bf16 v[32:47], v[216:219], v[208:211], v[32:47]
	ds_read_b64_tr_b16 v[232:233], v13 offset:45056
	ds_read_b64_tr_b16 v[234:235], v13 offset:47104
	s_waitcnt lgkmcnt(6)
	v_mfma_f32_32x32x16_bf16 v[16:31], v[220:223], v[196:199], v[16:31]
	v_add_u32_e32 v15, v14, v175
	ds_read_b128 v[2:5], v15
	s_waitcnt lgkmcnt(5)
	v_mfma_f32_32x32x16_bf16 v[16:31], v[224:227], v[204:207], v[16:31]
	ds_read_b128 v[6:9], v15 offset:8192
	s_add_i32 m0, s72, s77
	s_nop 0
	global_load_lds_dword v172, s[68:69]
	s_waitcnt lgkmcnt(4)
	v_mfma_f32_32x32x16_bf16 v[16:31], v[228:231], v[200:203], v[16:31]
	v_add_u32_e32 v15, v14, v176
	ds_read_b128 v[212:215], v15
	s_waitcnt lgkmcnt(3)
	v_mfma_f32_32x32x16_bf16 v[16:31], v[232:235], v[208:211], v[16:31]
	ds_read_b128 v[216:219], v15 offset:8192
	s_waitcnt lgkmcnt(2)
	v_mfma_f32_32x32x16_bf16 v[96:111], v[2:5], v[112:115], v[96:111]
	v_add_u32_e32 v15, v14, v177
	ds_read_b128 v[220:223], v15
	v_mfma_f32_32x32x16_bf16 v[80:95], v[6:9], v[112:115], v[80:95]
	ds_read_b128 v[224:227], v15 offset:8192
	s_waitcnt lgkmcnt(2)
	v_mfma_f32_32x32x16_bf16 v[96:111], v[212:215], v[116:119], v[96:111]
	v_add_u32_e32 v15, v14, v178
	ds_read_b128 v[228:231], v15
	v_mfma_f32_32x32x16_bf16 v[80:95], v[216:219], v[116:119], v[80:95]
	ds_read_b128 v[232:235], v15 offset:8192
	s_waitcnt lgkmcnt(2)
	v_mfma_f32_32x32x16_bf16 v[96:111], v[220:223], v[120:123], v[96:111]
	v_add_u32_e32 v15, v14, v179
	ds_read_b128 v[2:5], v15
	v_mfma_f32_32x32x16_bf16 v[80:95], v[224:227], v[120:123], v[80:95]
	ds_read_b128 v[6:9], v15 offset:8192
	s_waitcnt lgkmcnt(2)
	v_mfma_f32_32x32x16_bf16 v[96:111], v[228:231], v[124:127], v[96:111]
	v_add_u32_e32 v15, v14, v180
	ds_read_b128 v[212:215], v15
	v_mfma_f32_32x32x16_bf16 v[80:95], v[232:235], v[124:127], v[80:95]
	ds_read_b128 v[216:219], v15 offset:8192
	s_waitcnt lgkmcnt(2)
	v_mfma_f32_32x32x16_bf16 v[96:111], v[2:5], v[128:131], v[96:111]
	v_add_u32_e32 v15, v14, v181
	ds_read_b128 v[220:223], v15
	v_mfma_f32_32x32x16_bf16 v[80:95], v[6:9], v[128:131], v[80:95]
	ds_read_b128 v[224:227], v15 offset:8192
	s_waitcnt lgkmcnt(2)
	v_mfma_f32_32x32x16_bf16 v[96:111], v[212:215], v[132:135], v[96:111]
	v_add_u32_e32 v15, v14, v182
	ds_read_b128 v[228:231], v15
	v_mfma_f32_32x32x16_bf16 v[80:95], v[216:219], v[132:135], v[80:95]
	ds_read_b128 v[232:235], v15 offset:8192
	s_waitcnt lgkmcnt(0)
	s_waitcnt vmcnt(5)
	s_barrier
	v_mfma_f32_32x32x16_bf16 v[96:111], v[220:223], v[136:139], v[96:111]
	v_mfma_f32_32x32x16_bf16 v[80:95], v[224:227], v[136:139], v[80:95]
	v_mfma_f32_32x32x16_bf16 v[96:111], v[228:231], v[140:143], v[96:111]
	v_mfma_f32_32x32x16_bf16 v[80:95], v[232:235], v[140:143], v[80:95]
	s_nop 7
	s_branch .Lfx_h1_joined

.Lfx_h1_joined:
	s_andn2_b64 vcc, exec, s[78:79]
	s_cbranch_vccnz .Lfx_h2_invis
	s_add_i32 m0, s74, s77
	s_nop 0
	global_load_lds_dwordx4 v188, s[30:31]
	v_max3_f32 v0, v96, v97, v80
	v_max3_f32 v2, v98, v99, v81
	v_max3_f32 v0, v0, v82, v83
	v_max3_f32 v2, v2, v102, v103
	v_max3_f32 v0, v0, v100, v101
	v_max3_f32 v2, v2, v86, v87
	v_max3_f32 v0, v0, v84, v85
	v_max3_f32 v2, v2, v106, v107
	v_max3_f32 v0, v0, v104, v105
	v_max3_f32 v2, v2, v90, v91
	v_max3_f32 v0, v0, v88, v89
	v_max3_f32 v2, v2, v110, v111
	v_max3_f32 v0, v0, v108, v109
	v_max3_f32 v2, v2, v94, v95
	v_max3_f32 v0, v0, v92, v93
	v_max_f32_e32 v0, v0, v2
	v_mov_b32_e32 v2, v0
	s_nop 1
	v_permlane32_swap_b32_e32 v0, v2
	v_max_f32_e32 v0, v0, v2
	v_add_f32_e32 v2, 0x41000000, v192
	v_cmp_gt_f32_e32 vcc, v0, v2
	s_cbranch_vccz .Lfx_sm_exp_v
	v_max_f32_e32 v0, v0, v0
	v_max_f32_e32 v2, v192, v192
	v_max_f32_e32 v2, v2, v0
	v_sub_f32_e32 v0, v192, v2
	v_exp_f32_e32 v0, v0
	v_mov_b32_e32 v192, v2
	v_mul_f32_e32 v162, v162, v0
	v_pk_mul_f32 v[78:79], v[78:79], v[0:1] op_sel_hi:[1,0]
	v_pk_mul_f32 v[76:77], v[76:77], v[0:1] op_sel_hi:[1,0]
	v_pk_mul_f32 v[74:75], v[74:75], v[0:1] op_sel_hi:[1,0]
	v_pk_mul_f32 v[72:73], v[72:73], v[0:1] op_sel_hi:[1,0]
	v_pk_mul_f32 v[70:71], v[70:71], v[0:1] op_sel_hi:[1,0]
	v_pk_mul_f32 v[68:69], v[68:69], v[0:1] op_sel_hi:[1,0]
	v_pk_mul_f32 v[66:67], v[66:67], v[0:1] op_sel_hi:[1,0]
	v_pk_mul_f32 v[64:65], v[64:65], v[0:1] op_sel_hi:[1,0]
	v_pk_mul_f32 v[62:63], v[62:63], v[0:1] op_sel_hi:[1,0]
	v_pk_mul_f32 v[60:61], v[60:61], v[0:1] op_sel_hi:[1,0]
	v_pk_mul_f32 v[58:59], v[58:59], v[0:1] op_sel_hi:[1,0]
	v_pk_mul_f32 v[56:57], v[56:57], v[0:1] op_sel_hi:[1,0]
	v_pk_mul_f32 v[54:55], v[54:55], v[0:1] op_sel_hi:[1,0]
	v_pk_mul_f32 v[52:53], v[52:53], v[0:1] op_sel_hi:[1,0]
	v_pk_mul_f32 v[50:51], v[50:51], v[0:1] op_sel_hi:[1,0]
	v_pk_mul_f32 v[48:49], v[48:49], v[0:1] op_sel_hi:[1,0]
	v_pk_mul_f32 v[46:47], v[46:47], v[0:1] op_sel_hi:[1,0]
	v_pk_mul_f32 v[44:45], v[44:45], v[0:1] op_sel_hi:[1,0]
	v_pk_mul_f32 v[42:43], v[42:43], v[0:1] op_sel_hi:[1,0]
	v_pk_mul_f32 v[40:41], v[40:41], v[0:1] op_sel_hi:[1,0]
	v_pk_mul_f32 v[38:39], v[38:39], v[0:1] op_sel_hi:[1,0]
	v_pk_mul_f32 v[36:37], v[36:37], v[0:1] op_sel_hi:[1,0]
	v_pk_mul_f32 v[34:35], v[34:35], v[0:1] op_sel_hi:[1,0]
	v_pk_mul_f32 v[32:33], v[32:33], v[0:1] op_sel_hi:[1,0]
	v_pk_mul_f32 v[30:31], v[30:31], v[0:1] op_sel_hi:[1,0]
	v_pk_mul_f32 v[28:29], v[28:29], v[0:1] op_sel_hi:[1,0]
	v_pk_mul_f32 v[26:27], v[26:27], v[0:1] op_sel_hi:[1,0]
	v_pk_mul_f32 v[24:25], v[24:25], v[0:1] op_sel_hi:[1,0]
	v_pk_mul_f32 v[22:23], v[22:23], v[0:1] op_sel_hi:[1,0]
	v_pk_mul_f32 v[20:21], v[20:21], v[0:1] op_sel_hi:[1,0]
	v_pk_mul_f32 v[18:19], v[18:19], v[0:1] op_sel_hi:[1,0]
	v_pk_mul_f32 v[16:17], v[16:17], v[0:1] op_sel_hi:[1,0]
